# indexer: single looped copy + hand-written software-pipelined scoring loop (LDS-DMA tiles, MFMA beside VALU, out-of-line compaction)
# speedup vs baseline: 1.0365x; 1.0365x over previous
; #define LAS __attribute__((address_space(3)))
; __device__ __forceinline__ void indexer_block16(const bf16_t* __restrict__ Z, const bf16_t* __restrict__ KI, int* __restrict__ SEL, int qb, LAS unsigned char* lds, int wave) {
;     const int lane = lane_id(), tid = wave * 64 + lane, half = lane >> 5, r = lane & 31;
;     LAS u32x2* wbuf = (LAS u32x2*)lds + wave * 1536;
;     LAS unsigned char* tiles = lds + 98304;
;     LAS int* flags = (LAS int*)(lds + 98304 + 32768);
;     const int tA = qb * 16 + wave * 2, tmine = tA + half;
;     bf16x8 Af[4];
;     { const int aq = tA + ((r >> 2) & 1), ah = (r >> 3) * 4 + (r & 3);
;       const bf16_t* ap = Z + (size_t)aq * ZLD + OFF_QI + ah * 64 + half * 8;
; #pragma unroll
;       for (int kk = 0; kk < 4; ++kk) Af[kk] = *(const bf16x8*)(ap + kk * 16); }
;     float wq[16];
;     { const u32x4* wp = (const u32x4*)(Z + (size_t)tmine * ZLD + OFF_WI); const u32x4 a = wp[0], b = wp[1];
;       wq[0] = bf_lo(a.x); wq[1] = bf_hi(a.x); wq[2] = bf_lo(a.y); wq[3] = bf_hi(a.y); wq[4] = bf_lo(a.z); wq[5] = bf_hi(a.z); wq[6] = bf_lo(a.w); wq[7] = bf_hi(a.w);
;       wq[8] = bf_lo(b.x); wq[9] = bf_hi(b.x); wq[10] = bf_lo(b.y); wq[11] = bf_hi(b.y); wq[12] = bf_lo(b.z); wq[13] = bf_hi(b.z); wq[14] = bf_lo(b.w); wq[15] = bf_hi(b.w);
; #pragma unroll
;       for (int i = 0; i < 16; ++i) wq[i] *= 0.03125f; }
;     const int ntiles = (qb * 16 + 16 + 127) >> 7;
;     float tau = -__builtin_inff(); int cntA = 0, cntB = 0;
;     const u32x4* gsrc = (const u32x4*)KI + tid;
;     { const u32x4 g0 = gsrc[0], g1 = gsrc[512]; *(LAS u32x4*)(tiles + tid * 16) = g0; *(LAS u32x4*)(tiles + 8192 + tid * 16) = g1; }
;     __syncthreads();
; #pragma unroll 1
;     for (int i = 0; i < ntiles; ++i) {
;         u32x4 g0 = {0u, 0u, 0u, 0u}, g1 = {0u, 0u, 0u, 0u};
;         const bool more = (i + 1 < ntiles);
;         if (more) { g0 = gsrc[(size_t)(i + 1) * 1024]; g1 = gsrc[(size_t)(i + 1) * 1024 + 512]; }
;         const LAS unsigned char* tb = tiles + (i & 1) * 16384 + lane * 16;
;         float sc[4];
; #pragma unroll
;         for (int st = 0; st < 4; ++st) {
;             bf16x8 Bc[4];
; #pragma unroll
;             for (int kk = 0; kk < 4; ++kk) Bc[kk] = *(const LAS bf16x8*)(tb + (st * 4 + kk) * 1024);
;             f32x16 acc = {0.f, 0.f, 0.f, 0.f, 0.f, 0.f, 0.f, 0.f, 0.f, 0.f, 0.f, 0.f, 0.f, 0.f, 0.f, 0.f};
; #pragma unroll
.LBB0_353:
	s_cmp_lg_u32 s4, s0
	s_mov_b64 s[6:7], -1
	s_cbranch_scc0 .LBB0_1165
	s_mov_b32 s48, 0
	s_barrier
	s_branch .LBB0_357
.LBB0_356:
	s_add_i32 s48, s48, s62
	s_cmpk_lt_i32 s48, 0x200
	s_cbranch_scc0 .LBB0_1164
.LBB0_357:
	s_add_i32 s4, s48, s2
	s_cmpk_gt_i32 s4, 0x1ff
	s_cbranch_scc1 .LBB0_356
	s_lshl_b32 s49, s4, 4
	s_mov_b32 s98, 0
.Lidx_pass:
	v_mbcnt_lo_u32_b32 v100, -1, 0
	v_mbcnt_hi_u32_b32 v100, -1, v100
	s_nop 1
	s_add_i32 s92, s49, s72
	v_lshrrev_b32_e32 v0, 2, v100
	v_and_or_b32 v2, v0, 1, s92
	v_lshrrev_b32_e32 v0, 1, v100
	v_and_b32_e32 v1, 3, v100
	v_ashrrev_i32_e32 v8, 5, v100
	v_and_or_b32 v4, v0, 12, v1
	v_mov_b64_e32 v[0:1], s[42:43]
	v_mad_i64_i32 v[2:3], s[4:5], v2, s81, v[0:1]
	v_lshlrev_b32_e32 v90, 7, v4
	v_lshlrev_b32_e32 v4, 3, v8
	v_lshl_add_u64 v[2:3], v[2:3], 0, v[90:91]
	v_ashrrev_i32_e32 v5, 31, v4
	v_lshl_add_u64 v[2:3], v[4:5], 1, v[2:3]
	v_lshl_add_u64 v[18:19], v[2:3], 0, s[84:85]
	v_add_co_u32_e32 v2, vcc, s83, v2
	v_add_u32_e32 v90, s92, v8
	s_nop 0
	v_addc_co_u32_e32 v3, vcc, 0, v3, vcc
	v_mad_i64_i32 v[0:1], s[4:5], v90, s81, v[0:1]
	v_add_u32_e32 v20, s33, v100
	v_add_co_u32_e32 v4, vcc, s83, v0
	v_ashrrev_i32_e32 v21, 31, v20
	s_nop 0
	v_addc_co_u32_e32 v5, vcc, 0, v1, vcc
	v_lshl_add_u64 v[102:103], v[20:21], 4, s[56:57]
	v_add_co_u32_e32 v10, vcc, s83, v102
	v_lshl_add_u64 v[0:1], v[0:1], 0, s[88:89]
	s_nop 0
	v_addc_co_u32_e32 v11, vcc, 0, v103, vcc
	global_load_dwordx4 v[4:7], v[4:5], off offset:2176
	s_nop 0
	global_load_dwordx4 v[10:13], v[10:11], off
	s_nop 0
	global_load_dwordx4 v[64:67], v[18:19], off offset:32
	global_load_dwordx4 v[14:17], v[102:103], off
	global_load_dwordx4 v[68:71], v[18:19], off offset:64
	global_load_dwordx4 v[72:75], v[18:19], off offset:96
	global_load_dwordx4 v[76:79], v[2:3], off
	s_nop 0
	global_load_dwordx4 v[0:3], v[0:1], off offset:16
	s_add_i32 s4, s49, 0x8f
	s_ashr_i32 s93, s4, 7
	v_lshl_add_u32 v9, v20, 4, 0
	s_mov_b32 s74, 0
	v_add_u32_e32 v101, 0x18000, v9
	v_add_u32_e32 v9, 0x1a000, v9
	s_cmp_lt_i32 s93, 1
	s_mov_b32 s75, 0
	s_waitcnt vmcnt(6)
	ds_write_b128 v9, v[10:13]
	s_waitcnt vmcnt(4)
	ds_write_b128 v101, v[14:17]
	s_waitcnt lgkmcnt(0)
	s_barrier
	s_cbranch_scc1 .LBB0_573
	s_waitcnt vmcnt(0)
	v_lshlrev_b32_e32 v14, 16, v0
	v_and_b32_e32 v15, 0xffff0000, v0
	v_lshlrev_b32_e32 v0, 16, v1
	v_and_b32_e32 v1, 0xffff0000, v1
	v_pk_mul_f32 v[114:115], v[0:1], s[90:91] op_sel_hi:[1,0]
	s_add_i32 s4, 0, 0x18000
	v_mul_lo_u32 v0, v8, s79
	v_lshlrev_b32_e32 v10, 16, v4
	v_and_b32_e32 v11, 0xffff0000, v4
	v_lshlrev_b32_e32 v4, 16, v5
	v_and_b32_e32 v5, 0xffff0000, v5
	v_lshlrev_b32_e32 v12, 16, v6
	v_and_b32_e32 v13, 0xffff0000, v6
	v_lshlrev_b32_e32 v6, 16, v7
	v_and_b32_e32 v7, 0xffff0000, v7
	v_lshlrev_b32_e32 v16, 16, v2
	v_and_b32_e32 v17, 0xffff0000, v2
	v_lshlrev_b32_e32 v2, 16, v3
	v_and_b32_e32 v3, 0xffff0000, v3
	v_lshl_add_u32 v125, v100, 4, s4
	v_add_u32_e32 v126, s97, v0
	v_and_b32_e32 v0, 7, v100
	s_add_i32 s4, 0, 0x20000
	v_and_b32_e32 v124, 31, v100
	v_pk_mul_f32 v[104:105], v[10:11], s[90:91] op_sel_hi:[1,0]
	v_pk_mul_f32 v[106:107], v[4:5], s[90:91] op_sel_hi:[1,0]
	v_pk_mul_f32 v[108:109], v[12:13], s[90:91] op_sel_hi:[1,0]
	v_pk_mul_f32 v[110:111], v[6:7], s[90:91] op_sel_hi:[1,0]
	v_pk_mul_f32 v[112:113], v[14:15], s[90:91] op_sel_hi:[1,0]
	v_pk_mul_f32 v[116:117], v[16:17], s[90:91] op_sel_hi:[1,0]
	v_pk_mul_f32 v[118:119], v[2:3], s[90:91] op_sel_hi:[1,0]
	v_cmp_gt_u32_e64 s[6:7], 32, v100
	v_cmp_lt_u32_e64 s[8:9], 31, v100
	v_cmp_eq_u32_e64 s[10:11], 0, v100
	v_lshl_add_u32 v127, v0, 2, s4
	v_mov_b32_e32 v128, 0xff800000
	s_mov_b32 s12, 0
	s_lshl_b32 s32, s33, 4
	s_add_i32 s32, s32, 0x18000
	v_add_u32_e32 v221, s33, v100
	v_lshlrev_b32_e32 v221, 4, v221
	v_add_u32_e32 v222, 0x2000, v221
	s_mov_b32 s95, 0
	v_mov_b32_e32 v219, v125
	v_mov_b32_e32 v223, v124
	v_mov_b32_e32 v218, s91
	v_mov_b32_e32 v224, v127
	s_cmp_lt_i32 s93, 2
	s_cbranch_scc1 .Lidx_nodma1
	s_add_u32 s100, s56, 0x4000
	s_addc_u32 s101, s57, 0
	s_add_i32 m0, s32, 0x4000
	s_nop 0
	global_load_lds_dwordx4 v221, s[100:101]
	s_add_i32 m0, s32, 0x6000
	s_nop 0
	global_load_lds_dwordx4 v222, s[100:101]
.Lidx_nodma1:
	ds_read_b128 v[180:183], v219 offset:0
	ds_read_b128 v[184:187], v219 offset:1024
	ds_read_b128 v[188:191], v219 offset:2048
	ds_read_b128 v[192:195], v219 offset:3072
	ds_read_b128 v[196:199], v219 offset:4096
	ds_read_b128 v[200:203], v219 offset:5120
	ds_read_b128 v[204:207], v219 offset:6144
	ds_read_b128 v[208:211], v219 offset:7168
	s_waitcnt lgkmcnt(4)
	v_mfma_f32_32x32x16_bf16 v[148:163], v[76:79], v[180:183], 0
	v_mfma_f32_32x32x16_bf16 v[148:163], v[64:67], v[184:187], v[148:163]
	v_mfma_f32_32x32x16_bf16 v[148:163], v[68:71], v[188:191], v[148:163]
	v_mfma_f32_32x32x16_bf16 v[148:163], v[72:75], v[192:195], v[148:163]
	s_nop 7
	s_nop 3
	s_cmp_lt_i32 s93, 2
	s_cbranch_scc1 .Lidx_last
; __device__ __forceinline__ void indexer_block16(const bf16_t* __restrict__ Z, const bf16_t* __restrict__ KI, int* __restrict__ SEL, int qb, LAS unsigned char* lds, int wave) {
;     ...
;         if (more) { g0 = gsrc[(size_t)(i + 1) * 1024]; g1 = gsrc[(size_t)(i + 1) * 1024 + 512]; }
;         const LAS unsigned char* tb = tiles + (i & 1) * 16384 + lane * 16;
;         float sc[4];
; #pragma unroll
;         for (int st = 0; st < 4; ++st) {
;             bf16x8 Bc[4];
; #pragma unroll
;             for (int kk = 0; kk < 4; ++kk) Bc[kk] = *(const LAS bf16x8*)(tb + (st * 4 + kk) * 1024);
;             f32x16 acc = {0.f, 0.f, 0.f, 0.f, 0.f, 0.f, 0.f, 0.f, 0.f, 0.f, 0.f, 0.f, 0.f, 0.f, 0.f, 0.f};
; #pragma unroll
;             for (int kk = 0; kk < 4; ++kk) acc = __builtin_amdgcn_mfma_f32_32x32x16_bf16(Af[kk], Bc[kk], acc, 0, 0, 0);
;             float s0 = 0.f, s1 = 0.f;
; #pragma unroll
;             for (int h = 0; h < 16; h += 2) { const int b0 = __float_as_int(acc[h]), b1 = __float_as_int(acc[h + 1]);
;                 s0 = fmaf(wq[h], __int_as_float(b0 > 0 ? b0 : 0), s0); s1 = fmaf(wq[h + 1], __int_as_float(b1 > 0 ? b1 : 0), s1); }
;             sc[st] = s0 + s1;
;     ...
;             { f32x16 acc2 = {0.f, 0.f, 0.f, 0.f, 0.f, 0.f, 0.f, 0.f, 0.f, 0.f, 0.f, 0.f, 0.f, 0.f, 0.f, 0.f};
; #pragma unroll
;               for (int kk = 0; kk < 4; ++kk) acc2 = __builtin_amdgcn_mfma_f32_32x32x16_bf16(Af[kk], Bc[3 - kk], acc2, 0, 0, 0);
;               float t0 = 0.f, t1 = 0.f;
; #pragma unroll
;               for (int h = 0; h < 16; h += 2) { const int b0 = __float_as_int(acc2[h]), b1 = __float_as_int(acc2[h + 1]);
;                   t0 = fmaf(wq[h], __int_as_float(b0 > 0 ? b0 : 0), t0); t1 = fmaf(wq[h + 1], __int_as_float(b1 > 0 ? b1 : 0), t1); }
;               asm volatile("" :: "v"(t0 + t1)); }
;     ...
;         }
; #pragma unroll
;         for (int st = 0; st < 4; ++st) {
;             const int key = i * 128 + st * 32 + r;
;             const bool pass = (key <= tmine) && (sc[st] > tau);
;             const unsigned long long mk = __builtin_amdgcn_ballot_w64(pass);
;             if (mk != 0ull) {
;                 const unsigned lo = (unsigned)mk, hi = (unsigned)(mk >> 32);
;                 const int pre = half ? __builtin_amdgcn_mbcnt_hi(hi, 0) : __builtin_amdgcn_mbcnt_lo(lo, 0);
;                 const int base = half ? cntB : cntA;
.Lidx_tile:
	ds_read_b128 v[180:183], v219 offset:8192
	ds_read_b128 v[184:187], v219 offset:9216
	ds_read_b128 v[188:191], v219 offset:10240
	ds_read_b128 v[192:195], v219 offset:11264
	s_waitcnt lgkmcnt(4)
	v_mfma_f32_32x32x16_bf16 v[164:179], v[76:79], v[196:199], 0
	v_max_i32_e32 v148, 0, v148
	v_max_i32_e32 v149, 0, v149
	v_fma_f32 v212, v104, v148, 0
	v_fma_f32 v214, v105, v149, 0
	v_max_i32_e32 v150, 0, v150
	v_max_i32_e32 v151, 0, v151
	v_fmac_f32_e32 v212, v106, v150
	v_fmac_f32_e32 v214, v107, v151
	v_max_i32_e32 v152, 0, v152
	v_mfma_f32_32x32x16_bf16 v[164:179], v[64:67], v[200:203], v[164:179]
	v_max_i32_e32 v153, 0, v153
	v_fmac_f32_e32 v212, v108, v152
	v_fmac_f32_e32 v214, v109, v153
	v_max_i32_e32 v154, 0, v154
	v_max_i32_e32 v155, 0, v155
	v_fmac_f32_e32 v212, v110, v154
	v_fmac_f32_e32 v214, v111, v155
	v_max_i32_e32 v156, 0, v156
	v_mfma_f32_32x32x16_bf16 v[164:179], v[68:71], v[204:207], v[164:179]
	v_max_i32_e32 v157, 0, v157
	v_fmac_f32_e32 v212, v112, v156
	v_fmac_f32_e32 v214, v113, v157
	v_max_i32_e32 v158, 0, v158
	v_max_i32_e32 v159, 0, v159
	v_fmac_f32_e32 v212, v114, v158
	v_fmac_f32_e32 v214, v115, v159
	v_max_i32_e32 v160, 0, v160
	v_mfma_f32_32x32x16_bf16 v[164:179], v[72:75], v[208:211], v[164:179]
	v_max_i32_e32 v161, 0, v161
	v_fmac_f32_e32 v212, v116, v160
	v_fmac_f32_e32 v214, v117, v161
	v_max_i32_e32 v162, 0, v162
	v_max_i32_e32 v163, 0, v163
	v_fmac_f32_e32 v212, v118, v162
	v_fmac_f32_e32 v214, v119, v163
	v_add_f32_e32 v212, v212, v214
	v_cmp_gt_f32_e32 vcc, v212, v128
	s_cbranch_vccz .Lidx_skip_a
	v_mov_b32_e32 v213, v223
	v_mbcnt_lo_u32_b32 v215, vcc_lo, 0
	v_mbcnt_hi_u32_b32 v216, vcc_hi, 0
	v_add_lshl_u32 v215, v215, s74, 3
	v_add_lshl_u32 v216, v216, s75, 3
	v_cndmask_b32_e64 v215, v216, v215, s[6:7]
	v_add_u32_e32 v215, v126, v215
	s_mov_b64 exec, vcc
	ds_write_b64 v215, v[212:213]
	s_mov_b64 exec, -1
	s_bcnt1_i32_b32 s4, vcc_lo
	s_bcnt1_i32_b32 s5, vcc_hi
	s_add_i32 s74, s74, s4
	s_add_i32 s75, s75, s5
.Lidx_skip_a:
	ds_read_b128 v[196:199], v219 offset:12288
	ds_read_b128 v[200:203], v219 offset:13312
	ds_read_b128 v[204:207], v219 offset:14336
	ds_read_b128 v[208:211], v219 offset:15360
	s_waitcnt lgkmcnt(4)
	v_mfma_f32_32x32x16_bf16 v[148:163], v[76:79], v[180:183], 0
	v_max_i32_e32 v164, 0, v164
	v_max_i32_e32 v165, 0, v165
	v_fma_f32 v212, v104, v164, 0
	v_fma_f32 v214, v105, v165, 0
	v_max_i32_e32 v166, 0, v166
	v_max_i32_e32 v167, 0, v167
	v_fmac_f32_e32 v212, v106, v166
	v_fmac_f32_e32 v214, v107, v167
	v_max_i32_e32 v168, 0, v168
	v_mfma_f32_32x32x16_bf16 v[148:163], v[64:67], v[184:187], v[148:163]
	v_max_i32_e32 v169, 0, v169
	v_fmac_f32_e32 v212, v108, v168
	v_fmac_f32_e32 v214, v109, v169
	v_max_i32_e32 v170, 0, v170
	v_max_i32_e32 v171, 0, v171
	v_fmac_f32_e32 v212, v110, v170
	v_fmac_f32_e32 v214, v111, v171
	v_max_i32_e32 v172, 0, v172
	v_mfma_f32_32x32x16_bf16 v[148:163], v[68:71], v[188:191], v[148:163]
	v_max_i32_e32 v173, 0, v173
	v_fmac_f32_e32 v212, v112, v172
	v_fmac_f32_e32 v214, v113, v173
	v_max_i32_e32 v174, 0, v174
	v_max_i32_e32 v175, 0, v175
	v_fmac_f32_e32 v212, v114, v174
	v_fmac_f32_e32 v214, v115, v175
	v_max_i32_e32 v176, 0, v176
	v_mfma_f32_32x32x16_bf16 v[148:163], v[72:75], v[192:195], v[148:163]
	v_max_i32_e32 v177, 0, v177
	v_fmac_f32_e32 v212, v116, v176
	v_fmac_f32_e32 v214, v117, v177
	v_max_i32_e32 v178, 0, v178
	v_max_i32_e32 v179, 0, v179
	v_fmac_f32_e32 v212, v118, v178
	v_fmac_f32_e32 v214, v119, v179
	v_add_f32_e32 v212, v212, v214
	v_cmp_gt_f32_e32 vcc, v212, v128
	s_cbranch_vccz .Lidx_skip_b
	v_or_b32_e32 v213, 32, v223
	v_mbcnt_lo_u32_b32 v215, vcc_lo, 0
	v_mbcnt_hi_u32_b32 v216, vcc_hi, 0
	v_add_lshl_u32 v215, v215, s74, 3
	v_add_lshl_u32 v216, v216, s75, 3
	v_cndmask_b32_e64 v215, v216, v215, s[6:7]
	v_add_u32_e32 v215, v126, v215
	s_mov_b64 exec, vcc
	ds_write_b64 v215, v[212:213]
	s_mov_b64 exec, -1
	s_bcnt1_i32_b32 s4, vcc_lo
	s_bcnt1_i32_b32 s5, vcc_hi
	s_add_i32 s74, s74, s4
	s_add_i32 s75, s75, s5
.Lidx_skip_b:
	s_max_i32 s4, s74, s75
	s_cmpk_gt_i32 s4, 0x280
	s_cselect_b32 s4, 1, 0
	v_mov_b32_e32 v217, s4
	s_mov_b64 exec, 1
	ds_write_b32 v218, v217
	s_mov_b64 exec, -1
	v_xor_b32_e32 v220, 0x4000, v219
	s_waitcnt vmcnt(0) lgkmcnt(0)
	s_barrier
	ds_read_b32 v217, v224
	s_add_i32 s4, s95, 2
	s_cmp_ge_i32 s4, s93
	s_cbranch_scc1 .Lidx_nodma
	s_lshl_b32 s4, s4, 14
	s_add_u32 s100, s56, s4
	s_addc_u32 s101, s57, 0
	s_and_b32 s5, s95, 1
	s_lshl_b32 s5, s5, 14
	s_add_i32 s5, s5, s32
	s_mov_b32 m0, s5
	s_nop 0
	global_load_lds_dwordx4 v221, s[100:101]
	s_add_i32 m0, s5, 0x2000
	s_nop 0
	global_load_lds_dwordx4 v222, s[100:101]
; __device__ __forceinline__ void indexer_block16(const bf16_t* __restrict__ Z, const bf16_t* __restrict__ KI, int* __restrict__ SEL, int qb, LAS unsigned char* lds, int wave) {
;     ...
;         for (int st = 0; st < 4; ++st) {
;             bf16x8 Bc[4];
; #pragma unroll
;             for (int kk = 0; kk < 4; ++kk) Bc[kk] = *(const LAS bf16x8*)(tb + (st * 4 + kk) * 1024);
;             f32x16 acc = {0.f, 0.f, 0.f, 0.f, 0.f, 0.f, 0.f, 0.f, 0.f, 0.f, 0.f, 0.f, 0.f, 0.f, 0.f, 0.f};
; #pragma unroll
;             for (int kk = 0; kk < 4; ++kk) acc = __builtin_amdgcn_mfma_f32_32x32x16_bf16(Af[kk], Bc[kk], acc, 0, 0, 0);
;             float s0 = 0.f, s1 = 0.f;
; #pragma unroll
;             for (int h = 0; h < 16; h += 2) { const int b0 = __float_as_int(acc[h]), b1 = __float_as_int(acc[h + 1]);
;                 s0 = fmaf(wq[h], __int_as_float(b0 > 0 ? b0 : 0), s0); s1 = fmaf(wq[h + 1], __int_as_float(b1 > 0 ? b1 : 0), s1); }
;             sc[st] = s0 + s1;
;     ...
;             { f32x16 acc2 = {0.f, 0.f, 0.f, 0.f, 0.f, 0.f, 0.f, 0.f, 0.f, 0.f, 0.f, 0.f, 0.f, 0.f, 0.f, 0.f};
; #pragma unroll
;               for (int kk = 0; kk < 4; ++kk) acc2 = __builtin_amdgcn_mfma_f32_32x32x16_bf16(Af[kk], Bc[3 - kk], acc2, 0, 0, 0);
;               float t0 = 0.f, t1 = 0.f;
; #pragma unroll
;               for (int h = 0; h < 16; h += 2) { const int b0 = __float_as_int(acc2[h]), b1 = __float_as_int(acc2[h + 1]);
;                   t0 = fmaf(wq[h], __int_as_float(b0 > 0 ? b0 : 0), t0); t1 = fmaf(wq[h + 1], __int_as_float(b1 > 0 ? b1 : 0), t1); }
;               asm volatile("" :: "v"(t0 + t1)); }
;     ...
;         }
; #pragma unroll
;         for (int st = 0; st < 4; ++st) {
;             const int key = i * 128 + st * 32 + r;
;             const bool pass = (key <= tmine) && (sc[st] > tau);
;             const unsigned long long mk = __builtin_amdgcn_ballot_w64(pass);
;             if (mk != 0ull) {
;                 const unsigned lo = (unsigned)mk, hi = (unsigned)(mk >> 32);
;                 const int pre = half ? __builtin_amdgcn_mbcnt_hi(hi, 0) : __builtin_amdgcn_mbcnt_lo(lo, 0);
;                 const int base = half ? cntB : cntA;
;                 if (pass) { u32x2 o; o.x = __float_as_uint(sc[st]); o.y = (unsigned)key; wbuf[half * 768 + base + pre] = o; }
;                 cntA += __builtin_popcount(lo); cntB += __builtin_popcount(hi);
;             }
;         }
.Lidx_nodma:
	ds_read_b128 v[180:183], v220 offset:0
	ds_read_b128 v[184:187], v220 offset:1024
	ds_read_b128 v[188:191], v220 offset:2048
	ds_read_b128 v[192:195], v220 offset:3072
	v_mfma_f32_32x32x16_bf16 v[164:179], v[76:79], v[196:199], 0
	v_max_i32_e32 v148, 0, v148
	v_max_i32_e32 v149, 0, v149
	v_fma_f32 v212, v104, v148, 0
	v_fma_f32 v214, v105, v149, 0
	v_max_i32_e32 v150, 0, v150
	v_max_i32_e32 v151, 0, v151
	v_fmac_f32_e32 v212, v106, v150
	v_fmac_f32_e32 v214, v107, v151
	v_max_i32_e32 v152, 0, v152
	v_max_i32_e32 v153, 0, v153
	v_mfma_f32_32x32x16_bf16 v[164:179], v[64:67], v[200:203], v[164:179]
	v_fmac_f32_e32 v212, v108, v152
	v_fmac_f32_e32 v214, v109, v153
	s_waitcnt lgkmcnt(4)
	v_cmp_ne_u32_e64 s[14:15], 0, v217
	v_xor_b32_e32 v218, 32, v218
	v_xor_b32_e32 v224, 32, v224
	v_max_i32_e32 v154, 0, v154
	v_max_i32_e32 v155, 0, v155
	v_fmac_f32_e32 v212, v110, v154
	v_mfma_f32_32x32x16_bf16 v[164:179], v[68:71], v[204:207], v[164:179]
	v_fmac_f32_e32 v214, v111, v155
	v_max_i32_e32 v156, 0, v156
	v_max_i32_e32 v157, 0, v157
	v_fmac_f32_e32 v212, v112, v156
	v_fmac_f32_e32 v214, v113, v157
	v_max_i32_e32 v158, 0, v158
	v_max_i32_e32 v159, 0, v159
	v_fmac_f32_e32 v212, v114, v158
	v_fmac_f32_e32 v214, v115, v159
	v_mfma_f32_32x32x16_bf16 v[164:179], v[72:75], v[208:211], v[164:179]
	v_max_i32_e32 v160, 0, v160
	v_max_i32_e32 v161, 0, v161
	v_fmac_f32_e32 v212, v116, v160
	v_fmac_f32_e32 v214, v117, v161
	v_max_i32_e32 v162, 0, v162
	v_max_i32_e32 v163, 0, v163
	v_fmac_f32_e32 v212, v118, v162
	v_fmac_f32_e32 v214, v119, v163
	v_add_f32_e32 v212, v212, v214
	v_cmp_gt_f32_e32 vcc, v212, v128
	s_cbranch_vccz .Lidx_skip_c
	v_or_b32_e32 v213, 64, v223
	v_mbcnt_lo_u32_b32 v215, vcc_lo, 0
	v_mbcnt_hi_u32_b32 v216, vcc_hi, 0
	v_add_lshl_u32 v215, v215, s74, 3
	v_add_lshl_u32 v216, v216, s75, 3
	v_cndmask_b32_e64 v215, v216, v215, s[6:7]
	v_add_u32_e32 v215, v126, v215
	s_mov_b64 exec, vcc
	ds_write_b64 v215, v[212:213]
	s_mov_b64 exec, -1
	s_bcnt1_i32_b32 s4, vcc_lo
	s_bcnt1_i32_b32 s5, vcc_hi
	s_add_i32 s74, s74, s4
	s_add_i32 s75, s75, s5
.Lidx_skip_c:
	s_cmp_lg_u64 s[14:15], 0
	s_cbranch_scc1 .Lidx_compact
.LBB0_571:
	ds_read_b128 v[196:199], v220 offset:4096
	ds_read_b128 v[200:203], v220 offset:5120
	ds_read_b128 v[204:207], v220 offset:6144
	ds_read_b128 v[208:211], v220 offset:7168
	s_waitcnt lgkmcnt(4)
	v_mfma_f32_32x32x16_bf16 v[148:163], v[76:79], v[180:183], 0
	v_max_i32_e32 v164, 0, v164
	v_max_i32_e32 v165, 0, v165
	v_fma_f32 v212, v104, v164, 0
	v_fma_f32 v214, v105, v165, 0
	v_max_i32_e32 v166, 0, v166
	v_max_i32_e32 v167, 0, v167
	v_fmac_f32_e32 v212, v106, v166
	v_fmac_f32_e32 v214, v107, v167
	v_max_i32_e32 v168, 0, v168
	v_mfma_f32_32x32x16_bf16 v[148:163], v[64:67], v[184:187], v[148:163]
	v_max_i32_e32 v169, 0, v169
	v_fmac_f32_e32 v212, v108, v168
	v_fmac_f32_e32 v214, v109, v169
	v_max_i32_e32 v170, 0, v170
	v_max_i32_e32 v171, 0, v171
	v_fmac_f32_e32 v212, v110, v170
	v_fmac_f32_e32 v214, v111, v171
	v_max_i32_e32 v172, 0, v172
	v_mfma_f32_32x32x16_bf16 v[148:163], v[68:71], v[188:191], v[148:163]
	v_max_i32_e32 v173, 0, v173
	v_fmac_f32_e32 v212, v112, v172
	v_fmac_f32_e32 v214, v113, v173
	v_max_i32_e32 v174, 0, v174
	v_max_i32_e32 v175, 0, v175
	v_fmac_f32_e32 v212, v114, v174
	v_fmac_f32_e32 v214, v115, v175
	v_max_i32_e32 v176, 0, v176
	v_mfma_f32_32x32x16_bf16 v[148:163], v[72:75], v[192:195], v[148:163]
	v_max_i32_e32 v177, 0, v177
	v_fmac_f32_e32 v212, v116, v176
	v_fmac_f32_e32 v214, v117, v177
	v_max_i32_e32 v178, 0, v178
	v_max_i32_e32 v179, 0, v179
	v_fmac_f32_e32 v212, v118, v178
	v_fmac_f32_e32 v214, v119, v179
	v_add_f32_e32 v212, v212, v214
	v_cmp_gt_f32_e32 vcc, v212, v128
	s_cbranch_vccz .Lidx_skip_d
	v_or_b32_e32 v213, 96, v223
	v_mbcnt_lo_u32_b32 v215, vcc_lo, 0
	v_mbcnt_hi_u32_b32 v216, vcc_hi, 0
	v_add_lshl_u32 v215, v215, s74, 3
	v_add_lshl_u32 v216, v216, s75, 3
	v_cndmask_b32_e64 v215, v216, v215, s[6:7]
	v_add_u32_e32 v215, v126, v215
	s_mov_b64 exec, vcc
	ds_write_b64 v215, v[212:213]
	s_mov_b64 exec, -1
	s_bcnt1_i32_b32 s4, vcc_lo
	s_bcnt1_i32_b32 s5, vcc_hi
	s_add_i32 s74, s74, s4
	s_add_i32 s75, s75, s5
.Lidx_skip_d:
	s_add_i32 s95, s95, 1
	v_mov_b32_e32 v219, v220
	v_add_u32_e32 v223, 0x80, v223
	s_add_i32 s4, s95, 1
	s_cmp_lt_i32 s4, s93
	s_cbranch_scc1 .Lidx_tile
.Lidx_last:
	ds_read_b128 v[180:183], v219 offset:8192
	ds_read_b128 v[184:187], v219 offset:9216
	ds_read_b128 v[188:191], v219 offset:10240
	ds_read_b128 v[192:195], v219 offset:11264
	s_waitcnt lgkmcnt(4)
	v_mfma_f32_32x32x16_bf16 v[164:179], v[76:79], v[196:199], 0
	v_max_i32_e32 v148, 0, v148
	v_max_i32_e32 v149, 0, v149
	v_fma_f32 v212, v104, v148, 0
	v_fma_f32 v214, v105, v149, 0
	v_max_i32_e32 v150, 0, v150
	v_max_i32_e32 v151, 0, v151
	v_fmac_f32_e32 v212, v106, v150
	v_fmac_f32_e32 v214, v107, v151
	v_max_i32_e32 v152, 0, v152
	v_mfma_f32_32x32x16_bf16 v[164:179], v[64:67], v[200:203], v[164:179]
	v_max_i32_e32 v153, 0, v153
	v_fmac_f32_e32 v212, v108, v152
	v_fmac_f32_e32 v214, v109, v153
	v_max_i32_e32 v154, 0, v154
	v_max_i32_e32 v155, 0, v155
	v_fmac_f32_e32 v212, v110, v154
	v_fmac_f32_e32 v214, v111, v155
	v_max_i32_e32 v156, 0, v156
	v_mfma_f32_32x32x16_bf16 v[164:179], v[68:71], v[204:207], v[164:179]
	v_max_i32_e32 v157, 0, v157
	v_fmac_f32_e32 v212, v112, v156
	v_fmac_f32_e32 v214, v113, v157
	v_max_i32_e32 v158, 0, v158
	v_max_i32_e32 v159, 0, v159
	v_fmac_f32_e32 v212, v114, v158
	v_fmac_f32_e32 v214, v115, v159
	v_max_i32_e32 v160, 0, v160
	v_mfma_f32_32x32x16_bf16 v[164:179], v[72:75], v[208:211], v[164:179]
	v_max_i32_e32 v161, 0, v161
	v_fmac_f32_e32 v212, v116, v160
	v_fmac_f32_e32 v214, v117, v161
	v_max_i32_e32 v162, 0, v162
	v_max_i32_e32 v163, 0, v163
	v_fmac_f32_e32 v212, v118, v162
	v_fmac_f32_e32 v214, v119, v163
	v_add_f32_e32 v212, v212, v214
	v_mov_b32_e32 v213, v223
	v_cmp_le_i32_e32 vcc, v213, v90
	v_cmp_gt_f32_e64 s[12:13], v212, v128
	s_and_b64 vcc, vcc, s[12:13]
	s_cbranch_vccz .Lidx_skip_la
	v_mbcnt_lo_u32_b32 v215, vcc_lo, 0
	v_mbcnt_hi_u32_b32 v216, vcc_hi, 0
	v_add_lshl_u32 v215, v215, s74, 3
	v_add_lshl_u32 v216, v216, s75, 3
	v_cndmask_b32_e64 v215, v216, v215, s[6:7]
	v_add_u32_e32 v215, v126, v215
	s_mov_b64 exec, vcc
	ds_write_b64 v215, v[212:213]
	s_mov_b64 exec, -1
	s_bcnt1_i32_b32 s4, vcc_lo
	s_bcnt1_i32_b32 s5, vcc_hi
	s_add_i32 s74, s74, s4
	s_add_i32 s75, s75, s5
; __device__ __forceinline__ void indexer_block16(const bf16_t* __restrict__ Z, const bf16_t* __restrict__ KI, int* __restrict__ SEL, int qb, LAS unsigned char* lds, int wave) {
;     ...
;         for (int st = 0; st < 4; ++st) {
;             bf16x8 Bc[4];
; #pragma unroll
;             for (int kk = 0; kk < 4; ++kk) Bc[kk] = *(const LAS bf16x8*)(tb + (st * 4 + kk) * 1024);
;             f32x16 acc = {0.f, 0.f, 0.f, 0.f, 0.f, 0.f, 0.f, 0.f, 0.f, 0.f, 0.f, 0.f, 0.f, 0.f, 0.f, 0.f};
; #pragma unroll
;             for (int kk = 0; kk < 4; ++kk) acc = __builtin_amdgcn_mfma_f32_32x32x16_bf16(Af[kk], Bc[kk], acc, 0, 0, 0);
;             float s0 = 0.f, s1 = 0.f;
; #pragma unroll
;             for (int h = 0; h < 16; h += 2) { const int b0 = __float_as_int(acc[h]), b1 = __float_as_int(acc[h + 1]);
;                 s0 = fmaf(wq[h], __int_as_float(b0 > 0 ? b0 : 0), s0); s1 = fmaf(wq[h + 1], __int_as_float(b1 > 0 ? b1 : 0), s1); }
;             sc[st] = s0 + s1;
;     ...
;             { f32x16 acc2 = {0.f, 0.f, 0.f, 0.f, 0.f, 0.f, 0.f, 0.f, 0.f, 0.f, 0.f, 0.f, 0.f, 0.f, 0.f, 0.f};
; #pragma unroll
;               for (int kk = 0; kk < 4; ++kk) acc2 = __builtin_amdgcn_mfma_f32_32x32x16_bf16(Af[kk], Bc[3 - kk], acc2, 0, 0, 0);
;               float t0 = 0.f, t1 = 0.f;
; #pragma unroll
;               for (int h = 0; h < 16; h += 2) { const int b0 = __float_as_int(acc2[h]), b1 = __float_as_int(acc2[h + 1]);
;                   t0 = fmaf(wq[h], __int_as_float(b0 > 0 ? b0 : 0), t0); t1 = fmaf(wq[h + 1], __int_as_float(b1 > 0 ? b1 : 0), t1); }
;               asm volatile("" :: "v"(t0 + t1)); }
;     ...
;         }
; #pragma unroll
;         for (int st = 0; st < 4; ++st) {
;             const int key = i * 128 + st * 32 + r;
;             const bool pass = (key <= tmine) && (sc[st] > tau);
;             const unsigned long long mk = __builtin_amdgcn_ballot_w64(pass);
;             if (mk != 0ull) {
;                 const unsigned lo = (unsigned)mk, hi = (unsigned)(mk >> 32);
;                 const int pre = half ? __builtin_amdgcn_mbcnt_hi(hi, 0) : __builtin_amdgcn_mbcnt_lo(lo, 0);
;                 const int base = half ? cntB : cntA;
;                 if (pass) { u32x2 o; o.x = __float_as_uint(sc[st]); o.y = (unsigned)key; wbuf[half * 768 + base + pre] = o; }
;                 cntA += __builtin_popcount(lo); cntB += __builtin_popcount(hi);
;             }
;         }
.Lidx_skip_la:
	ds_read_b128 v[196:199], v219 offset:12288
	ds_read_b128 v[200:203], v219 offset:13312
	ds_read_b128 v[204:207], v219 offset:14336
	ds_read_b128 v[208:211], v219 offset:15360
	s_waitcnt lgkmcnt(4)
	v_mfma_f32_32x32x16_bf16 v[148:163], v[76:79], v[180:183], 0
	v_max_i32_e32 v164, 0, v164
	v_max_i32_e32 v165, 0, v165
	v_fma_f32 v212, v104, v164, 0
	v_fma_f32 v214, v105, v165, 0
	v_max_i32_e32 v166, 0, v166
	v_max_i32_e32 v167, 0, v167
	v_fmac_f32_e32 v212, v106, v166
	v_fmac_f32_e32 v214, v107, v167
	v_max_i32_e32 v168, 0, v168
	v_mfma_f32_32x32x16_bf16 v[148:163], v[64:67], v[184:187], v[148:163]
	v_max_i32_e32 v169, 0, v169
	v_fmac_f32_e32 v212, v108, v168
	v_fmac_f32_e32 v214, v109, v169
	v_max_i32_e32 v170, 0, v170
	v_max_i32_e32 v171, 0, v171
	v_fmac_f32_e32 v212, v110, v170
	v_fmac_f32_e32 v214, v111, v171
	v_max_i32_e32 v172, 0, v172
	v_mfma_f32_32x32x16_bf16 v[148:163], v[68:71], v[188:191], v[148:163]
	v_max_i32_e32 v173, 0, v173
	v_fmac_f32_e32 v212, v112, v172
	v_fmac_f32_e32 v214, v113, v173
	v_max_i32_e32 v174, 0, v174
	v_max_i32_e32 v175, 0, v175
	v_fmac_f32_e32 v212, v114, v174
	v_fmac_f32_e32 v214, v115, v175
	v_max_i32_e32 v176, 0, v176
	v_mfma_f32_32x32x16_bf16 v[148:163], v[72:75], v[192:195], v[148:163]
	v_max_i32_e32 v177, 0, v177
	v_fmac_f32_e32 v212, v116, v176
	v_fmac_f32_e32 v214, v117, v177
	v_max_i32_e32 v178, 0, v178
	v_max_i32_e32 v179, 0, v179
	v_fmac_f32_e32 v212, v118, v178
	v_fmac_f32_e32 v214, v119, v179
	v_add_f32_e32 v212, v212, v214
	v_or_b32_e32 v213, 32, v223
	v_cmp_le_i32_e32 vcc, v213, v90
	v_cmp_gt_f32_e64 s[12:13], v212, v128
	s_and_b64 vcc, vcc, s[12:13]
	s_cbranch_vccz .Lidx_skip_lb
	v_mbcnt_lo_u32_b32 v215, vcc_lo, 0
	v_mbcnt_hi_u32_b32 v216, vcc_hi, 0
	v_add_lshl_u32 v215, v215, s74, 3
	v_add_lshl_u32 v216, v216, s75, 3
	v_cndmask_b32_e64 v215, v216, v215, s[6:7]
	v_add_u32_e32 v215, v126, v215
	s_mov_b64 exec, vcc
	ds_write_b64 v215, v[212:213]
	s_mov_b64 exec, -1
	s_bcnt1_i32_b32 s4, vcc_lo
	s_bcnt1_i32_b32 s5, vcc_hi
	s_add_i32 s74, s74, s4
	s_add_i32 s75, s75, s5
.Lidx_skip_lb:
	s_waitcnt lgkmcnt(0)
	v_mfma_f32_32x32x16_bf16 v[164:179], v[76:79], v[196:199], 0
	v_max_i32_e32 v148, 0, v148
	v_max_i32_e32 v149, 0, v149
	v_fma_f32 v212, v104, v148, 0
	v_fma_f32 v214, v105, v149, 0
	v_max_i32_e32 v150, 0, v150
	v_max_i32_e32 v151, 0, v151
	v_fmac_f32_e32 v212, v106, v150
	v_fmac_f32_e32 v214, v107, v151
	v_max_i32_e32 v152, 0, v152
	v_mfma_f32_32x32x16_bf16 v[164:179], v[64:67], v[200:203], v[164:179]
	v_max_i32_e32 v153, 0, v153
	v_fmac_f32_e32 v212, v108, v152
	v_fmac_f32_e32 v214, v109, v153
	v_max_i32_e32 v154, 0, v154
	v_max_i32_e32 v155, 0, v155
	v_fmac_f32_e32 v212, v110, v154
	v_fmac_f32_e32 v214, v111, v155
	v_max_i32_e32 v156, 0, v156
	v_mfma_f32_32x32x16_bf16 v[164:179], v[68:71], v[204:207], v[164:179]
	v_max_i32_e32 v157, 0, v157
	v_fmac_f32_e32 v212, v112, v156
	v_fmac_f32_e32 v214, v113, v157
	v_max_i32_e32 v158, 0, v158
	v_max_i32_e32 v159, 0, v159
	v_fmac_f32_e32 v212, v114, v158
	v_fmac_f32_e32 v214, v115, v159
	v_max_i32_e32 v160, 0, v160
	v_mfma_f32_32x32x16_bf16 v[164:179], v[72:75], v[208:211], v[164:179]
	v_max_i32_e32 v161, 0, v161
	v_fmac_f32_e32 v212, v116, v160
	v_fmac_f32_e32 v214, v117, v161
	v_max_i32_e32 v162, 0, v162
	v_max_i32_e32 v163, 0, v163
	v_fmac_f32_e32 v212, v118, v162
	v_fmac_f32_e32 v214, v119, v163
	v_add_f32_e32 v212, v212, v214
	v_or_b32_e32 v213, 64, v223
	v_cmp_le_i32_e32 vcc, v213, v90
	v_cmp_gt_f32_e64 s[12:13], v212, v128
	s_and_b64 vcc, vcc, s[12:13]
	s_cbranch_vccz .Lidx_skip_lc
	v_mbcnt_lo_u32_b32 v215, vcc_lo, 0
	v_mbcnt_hi_u32_b32 v216, vcc_hi, 0
	v_add_lshl_u32 v215, v215, s74, 3
	v_add_lshl_u32 v216, v216, s75, 3
	v_cndmask_b32_e64 v215, v216, v215, s[6:7]
	v_add_u32_e32 v215, v126, v215
	s_mov_b64 exec, vcc
	ds_write_b64 v215, v[212:213]
	s_mov_b64 exec, -1
	s_bcnt1_i32_b32 s4, vcc_lo
	s_bcnt1_i32_b32 s5, vcc_hi
	s_add_i32 s74, s74, s4
	s_add_i32 s75, s75, s5
.Lidx_skip_lc:
	s_nop 7
	s_nop 3
	v_max_i32_e32 v164, 0, v164
	v_max_i32_e32 v165, 0, v165
	v_fma_f32 v212, v104, v164, 0
	v_fma_f32 v214, v105, v165, 0
	v_max_i32_e32 v166, 0, v166
	v_max_i32_e32 v167, 0, v167
	v_fmac_f32_e32 v212, v106, v166
	v_fmac_f32_e32 v214, v107, v167
	v_max_i32_e32 v168, 0, v168
	v_max_i32_e32 v169, 0, v169
	v_fmac_f32_e32 v212, v108, v168
	v_fmac_f32_e32 v214, v109, v169
	v_max_i32_e32 v170, 0, v170
	v_max_i32_e32 v171, 0, v171
	v_fmac_f32_e32 v212, v110, v170
	v_fmac_f32_e32 v214, v111, v171
	v_max_i32_e32 v172, 0, v172
	v_max_i32_e32 v173, 0, v173
	v_fmac_f32_e32 v212, v112, v172
	v_fmac_f32_e32 v214, v113, v173
	v_max_i32_e32 v174, 0, v174
	v_max_i32_e32 v175, 0, v175
	v_fmac_f32_e32 v212, v114, v174
	v_fmac_f32_e32 v214, v115, v175
	v_max_i32_e32 v176, 0, v176
	v_max_i32_e32 v177, 0, v177
	v_fmac_f32_e32 v212, v116, v176
	v_fmac_f32_e32 v214, v117, v177
	v_max_i32_e32 v178, 0, v178
	v_max_i32_e32 v179, 0, v179
	v_fmac_f32_e32 v212, v118, v178
	v_fmac_f32_e32 v214, v119, v179
	v_add_f32_e32 v212, v212, v214
	v_or_b32_e32 v213, 96, v223
	v_cmp_le_i32_e32 vcc, v213, v90
	v_cmp_gt_f32_e64 s[12:13], v212, v128
	s_and_b64 vcc, vcc, s[12:13]
	s_cbranch_vccz .Lidx_skip_ld
	v_mbcnt_lo_u32_b32 v215, vcc_lo, 0
	v_mbcnt_hi_u32_b32 v216, vcc_hi, 0
	v_add_lshl_u32 v215, v215, s74, 3
	v_add_lshl_u32 v216, v216, s75, 3
	v_cndmask_b32_e64 v215, v216, v215, s[6:7]
	v_add_u32_e32 v215, v126, v215
	s_mov_b64 exec, vcc
	ds_write_b64 v215, v[212:213]
	s_mov_b64 exec, -1
	s_bcnt1_i32_b32 s4, vcc_lo
	s_bcnt1_i32_b32 s5, vcc_hi
	s_add_i32 s74, s74, s4
	s_add_i32 s75, s75, s5

; #define LAS __attribute__((address_space(3)))
; #define LDS_WAIT() asm volatile("s_waitcnt lgkmcnt(0)" ::: "memory")
; __device__ __forceinline__ int lane_id() { int l; asm volatile("v_mbcnt_lo_u32_b32 %0, -1, 0\n\tv_mbcnt_hi_u32_b32 %0, -1, %0\n\ts_nop 1" : "=v"(l)); return l; }
; __device__ __forceinline__ unsigned f2ord(float f) { const unsigned u = __float_as_uint(f); return u ^ ((u >> 31) ? 0xFFFFFFFFu : 0x80000000u); }
; __device__ __forceinline__ int topk_compact(LAS u32x2* buf, int cnt, float& tau) {
;     const int lane = lane_id();
;     LDS_WAIT();
;     unsigned key[12], idx[12];
;     unsigned kmin = 0xFFFFFFFFu, kmax = 0u;
; #pragma unroll
;     for (int j = 0; j < 12; ++j) { const int e = j * 64 + lane; const u32x2 v = buf[e]; const bool ok = e < cnt; const unsigned k = f2ord(__uint_as_float(v.x)); key[j] = ok ? k : 0u; idx[j] = v.y;
;         kmin = (ok && k < kmin) ? k : kmin; kmax = (ok && k > kmax) ? k : kmax; }
; #pragma unroll
;     for (int o = 1; o < 64; o <<= 1) { const unsigned a = (unsigned)__shfl_xor((int)kmin, o), b = (unsigned)__shfl_xor((int)kmax, o); kmin = a < kmin ? a : kmin; kmax = b > kmax ? b : kmax; }
;     const unsigned diff = (unsigned)__builtin_amdgcn_readfirstlane((int)(kmin ^ kmax));
;     int bit = diff ? (31 - __builtin_clz(diff)) : -1;
;     unsigned T = (bit >= 0) ? (unsigned)__builtin_amdgcn_readfirstlane((int)kmin) & ~((2u << bit) - 1u) : (unsigned)__builtin_amdgcn_readfirstlane((int)kmin);
.Lidx_compact:
	s_cmpk_lt_i32 s74, 0x101
	s_cbranch_scc1 .LBB0_485
	v_mbcnt_lo_u32_b32 v25, -1, 0
	v_mbcnt_hi_u32_b32 v25, -1, v25
	s_nop 1
	s_waitcnt lgkmcnt(0)
	s_nop 0
	v_lshl_add_u32 v0, v25, 3, s97
	ds_read2st64_b64 v[20:23], v0 offset1:1
	ds_read2st64_b64 v[8:11], v0 offset0:2 offset1:3
	v_add_u32_e32 v2, 64, v25
	v_cmp_gt_i32_e64 s[12:13], s74, v2
	ds_read2st64_b64 v[16:19], v0 offset0:4 offset1:5
	ds_read2st64_b64 v[12:15], v0 offset0:6 offset1:7
	s_waitcnt lgkmcnt(3)
	v_cmp_lt_i32_e32 vcc, -1, v20
	v_add_u32_e32 v27, 0x200, v25
	v_cmp_gt_i32_e64 s[26:27], s74, v27
	v_cndmask_b32_e32 v1, -1, v123, vcc
	v_xor_b32_e32 v1, v1, v20
	v_cmp_gt_i32_e32 vcc, s74, v25
	s_nop 1
	v_cndmask_b32_e32 v24, 0, v1, vcc
	v_cndmask_b32_e32 v1, -1, v1, vcc
	v_cmp_lt_i32_e32 vcc, -1, v22
	s_nop 1
	v_cndmask_b32_e32 v3, -1, v123, vcc
	v_xor_b32_e32 v20, v3, v22
	s_waitcnt lgkmcnt(2)
	v_cmp_lt_i32_e32 vcc, -1, v8
	v_min_u32_e32 v3, v20, v1
	v_cndmask_b32_e64 v1, v1, v3, s[12:13]
	v_cndmask_b32_e32 v4, -1, v123, vcc
	v_max_u32_e32 v2, v20, v24
	v_add_u32_e32 v3, 0x80, v25
	v_xor_b32_e32 v8, v4, v8
	v_cndmask_b32_e64 v2, v24, v2, s[12:13]
	v_min_u32_e32 v4, v8, v1
	v_cmp_gt_i32_e64 s[14:15], s74, v3
	v_cmp_lt_i32_e32 vcc, -1, v10
	v_max_u32_e32 v3, v8, v2
	v_cndmask_b32_e64 v1, v1, v4, s[14:15]
	v_cndmask_b32_e32 v4, -1, v123, vcc
	v_cndmask_b32_e64 v2, v2, v3, s[14:15]
	v_add_u32_e32 v3, 0xc0, v25
	v_xor_b32_e32 v10, v4, v10
	v_min_u32_e32 v4, v10, v1
	v_cmp_gt_i32_e64 s[16:17], s74, v3
	s_waitcnt lgkmcnt(1)
	v_cmp_lt_i32_e32 vcc, -1, v16
	v_max_u32_e32 v3, v10, v2
	v_cndmask_b32_e64 v1, v1, v4, s[16:17]
	v_cndmask_b32_e32 v4, -1, v123, vcc
	v_cndmask_b32_e64 v2, v2, v3, s[16:17]
	v_add_u32_e32 v3, 0x100, v25
	v_xor_b32_e32 v16, v4, v16
	v_min_u32_e32 v4, v16, v1
	v_cmp_gt_i32_e64 s[18:19], s74, v3
	v_cmp_lt_i32_e32 vcc, -1, v18
	v_max_u32_e32 v3, v16, v2
	v_cndmask_b32_e64 v1, v1, v4, s[18:19]
	v_cndmask_b32_e32 v4, -1, v123, vcc
	v_cndmask_b32_e64 v2, v2, v3, s[18:19]
	v_add_u32_e32 v3, 0x140, v25
	v_xor_b32_e32 v18, v4, v18
	v_min_u32_e32 v4, v18, v1
	v_cmp_gt_i32_e64 s[20:21], s74, v3
	s_waitcnt lgkmcnt(0)
	v_cmp_lt_i32_e32 vcc, -1, v12
	v_max_u32_e32 v3, v18, v2
	v_cndmask_b32_e64 v1, v1, v4, s[20:21]
	v_cndmask_b32_e32 v4, -1, v123, vcc
	v_cndmask_b32_e64 v2, v2, v3, s[20:21]
	v_add_u32_e32 v3, 0x180, v25
	v_xor_b32_e32 v12, v4, v12
	v_min_u32_e32 v4, v12, v1
	v_cmp_gt_i32_e64 s[22:23], s74, v3
	v_cmp_lt_i32_e32 vcc, -1, v14
	v_max_u32_e32 v3, v12, v2
	v_cndmask_b32_e64 v1, v1, v4, s[22:23]
	v_cndmask_b32_e32 v4, -1, v123, vcc
	v_cndmask_b32_e64 v2, v2, v3, s[22:23]
	v_add_u32_e32 v3, 0x1c0, v25
	v_xor_b32_e32 v14, v4, v14
	v_min_u32_e32 v4, v14, v1
	v_cmp_gt_i32_e64 s[24:25], s74, v3
	s_nop 1
	v_cndmask_b32_e64 v22, v1, v4, s[24:25]
	ds_read2st64_b64 v[4:7], v0 offset0:8 offset1:9
	v_max_u32_e32 v1, v14, v2
	v_cndmask_b32_e64 v26, v2, v1, s[24:25]
	ds_read2st64_b64 v[0:3], v0 offset0:10 offset1:11
	s_waitcnt lgkmcnt(1)
	v_cmp_lt_i32_e32 vcc, -1, v4
	s_nop 1
	v_cndmask_b32_e32 v28, -1, v123, vcc
	v_xor_b32_e32 v4, v28, v4
	v_min_u32_e32 v28, v4, v22
	v_cmp_lt_i32_e32 vcc, -1, v6
	v_cndmask_b32_e64 v22, v22, v28, s[26:27]
	v_max_u32_e32 v27, v4, v26
	v_cndmask_b32_e32 v28, -1, v123, vcc
	v_cndmask_b32_e64 v26, v26, v27, s[26:27]
	v_add_u32_e32 v27, 0x240, v25
	v_xor_b32_e32 v6, v28, v6
	v_min_u32_e32 v28, v6, v22
	v_cmp_gt_i32_e64 s[28:29], s74, v27
	s_waitcnt lgkmcnt(0)
	v_cmp_lt_i32_e32 vcc, -1, v0
	v_max_u32_e32 v27, v6, v26
	v_cndmask_b32_e64 v22, v22, v28, s[28:29]
	v_cndmask_b32_e32 v28, -1, v123, vcc
	v_cndmask_b32_e64 v26, v26, v27, s[28:29]
	v_add_u32_e32 v27, 0x280, v25
	v_xor_b32_e32 v0, v28, v0
	v_cmp_gt_i32_e64 s[30:31], s74, v27
	v_max_u32_e32 v27, v0, v26
	v_cmp_lt_i32_e32 vcc, -1, v2
	v_cndmask_b32_e64 v26, v26, v27, s[30:31]
	v_min_u32_e32 v28, v0, v22
	v_cndmask_b32_e32 v27, -1, v123, vcc
	v_add_u32_e32 v25, 0x2c0, v25
	v_xor_b32_e32 v2, v27, v2
	v_cndmask_b32_e64 v22, v22, v28, s[30:31]
	v_cmp_gt_i32_e64 s[34:35], s74, v25
	v_max_u32_e32 v25, v2, v26
	v_min_u32_e32 v27, v2, v22
	v_cndmask_b32_e64 v25, v26, v25, s[34:35]
	v_and_b32_e32 v26, 64, v144
	v_cndmask_b32_e64 v22, v22, v27, s[34:35]
	v_add_u32_e32 v26, 64, v26
	v_xor_b32_e32 v27, 1, v144
	v_cmp_lt_i32_e32 vcc, v27, v26
	s_nop 1
	v_cndmask_b32_e32 v27, v144, v27, vcc
	v_lshlrev_b32_e32 v27, 2, v27
	ds_bpermute_b32 v28, v27, v22
	ds_bpermute_b32 v27, v27, v25
	s_waitcnt lgkmcnt(1)
	v_min_u32_e32 v22, v28, v22
	s_waitcnt lgkmcnt(0)
	v_max_u32_e32 v25, v27, v25
	v_xor_b32_e32 v27, 2, v144
	v_cmp_lt_i32_e32 vcc, v27, v26
	s_nop 1
	v_cndmask_b32_e32 v27, v144, v27, vcc
	v_lshlrev_b32_e32 v27, 2, v27
	ds_bpermute_b32 v28, v27, v22
	ds_bpermute_b32 v27, v27, v25
	s_waitcnt lgkmcnt(1)
	v_min_u32_e32 v22, v28, v22
	s_waitcnt lgkmcnt(0)
	v_max_u32_e32 v25, v27, v25
	v_xor_b32_e32 v27, 4, v144
	v_cmp_lt_i32_e32 vcc, v27, v26
	s_nop 1
	v_cndmask_b32_e32 v27, v144, v27, vcc
	v_lshlrev_b32_e32 v27, 2, v27
	ds_bpermute_b32 v28, v27, v22
	ds_bpermute_b32 v27, v27, v25
	s_waitcnt lgkmcnt(1)
	v_min_u32_e32 v22, v28, v22
	s_waitcnt lgkmcnt(0)
	v_max_u32_e32 v25, v27, v25
	v_xor_b32_e32 v27, 8, v144
	v_cmp_lt_i32_e32 vcc, v27, v26
	s_nop 1
	v_cndmask_b32_e32 v27, v144, v27, vcc
	v_lshlrev_b32_e32 v27, 2, v27
	ds_bpermute_b32 v28, v27, v22
	ds_bpermute_b32 v27, v27, v25
	s_waitcnt lgkmcnt(1)
	v_min_u32_e32 v22, v28, v22
	s_waitcnt lgkmcnt(0)
	v_max_u32_e32 v25, v27, v25
	v_xor_b32_e32 v27, 16, v144
	v_cmp_lt_i32_e32 vcc, v27, v26
	s_nop 1
	v_cndmask_b32_e32 v27, v144, v27, vcc
	v_lshlrev_b32_e32 v27, 2, v27
	ds_bpermute_b32 v28, v27, v22
	ds_bpermute_b32 v27, v27, v25
	s_waitcnt lgkmcnt(1)
	v_min_u32_e32 v22, v28, v22
	s_waitcnt lgkmcnt(0)
	v_max_u32_e32 v25, v27, v25
	v_xor_b32_e32 v27, 32, v144
	v_cmp_lt_i32_e32 vcc, v27, v26
	s_nop 1
	v_cndmask_b32_e32 v26, v144, v27, vcc
	v_lshlrev_b32_e32 v26, 2, v26
	ds_bpermute_b32 v27, v26, v22
	ds_bpermute_b32 v26, v26, v25
	s_waitcnt lgkmcnt(1)
	v_min_u32_e32 v22, v27, v22
	s_waitcnt lgkmcnt(0)
	v_max_u32_e32 v25, v26, v25
	v_xor_b32_e32 v25, v22, v25
	s_nop 0
	v_readfirstlane_b32 s5, v25
	s_cmp_lg_u32 s5, 0
	s_flbit_i32_b32 s4, s5
	s_cselect_b64 s[36:37], -1, 0
	s_xor_b32 s4, s4, 31
	s_cmp_eq_u32 s5, 0
	s_cbranch_scc1 .LBB0_456
	v_readfirstlane_b32 s5, v22
	s_lshl_b32 s94, -2, s4
	s_and_b32 s5, s5, s94
	s_cbranch_execnz .LBB0_395

; __device__ __forceinline__ int mbcnt64(unsigned long long m) { return __builtin_amdgcn_mbcnt_hi((unsigned)(m >> 32), __builtin_amdgcn_mbcnt_lo((unsigned)m, 0)); }
; __device__ __forceinline__ unsigned ord2bits(unsigned k) { return (k & 0x80000000u) ? (k ^ 0x80000000u) : ~k; }
; __device__ __forceinline__ int topk_compact(LAS u32x2* buf, int cnt, float& tau) {
;     ...
;         for (int j = 0; j < 12; ++j) { const bool g = key[j] > T; const unsigned long long mk = __builtin_amdgcn_ballot_w64(g); const int pos = base + mbcnt64(mk);
;             if (g) { u32x2 o; o.x = ord2bits(key[j]); o.y = idx[j]; buf[pos] = o; } base += __builtin_popcountll(mk); }
; #pragma unroll
;         for (int j = 0; j < 12; ++j) { const bool g = key[j] == T; const unsigned long long mk = __builtin_amdgcn_ballot_w64(g); const int pos = base + mbcnt64(mk);
;             if (g && pos < 256) { u32x2 o; o.x = ord2bits(key[j]); o.y = idx[j]; buf[pos] = o; } base += __builtin_popcountll(mk); }
;     }
.LBB0_423:
	s_or_b64 exec, exec, s[16:17]
	s_bcnt1_i32_b64 s5, vcc
	v_cmp_eq_u32_e32 vcc, v24, v25
	s_add_i32 s4, s4, s5
	s_nop 0
	v_mbcnt_lo_u32_b32 v0, vcc_lo, 0
	v_mbcnt_hi_u32_b32 v0, vcc_hi, v0
	v_add_u32_e32 v0, s4, v0
	v_cmp_gt_i32_e64 s[12:13], s38, v0
	s_and_b64 s[12:13], vcc, s[12:13]
	s_and_saveexec_b64 s[16:17], s[12:13]
	v_cmp_lt_i32_e64 s[12:13], -1, v24
	v_lshl_add_u32 v0, v0, 3, s97
	s_nop 0
	v_cndmask_b32_e64 v2, v123, -1, s[12:13]
	v_xor_b32_e32 v20, v2, v24
	ds_write_b64 v0, v[20:21]
	s_or_b64 exec, exec, s[16:17]
	s_bcnt1_i32_b64 s5, vcc
	v_cmp_eq_u32_e32 vcc, v36, v25
	s_add_i32 s4, s4, s5
	s_nop 0
	v_mbcnt_lo_u32_b32 v0, vcc_lo, 0
	v_mbcnt_hi_u32_b32 v0, vcc_hi, v0
	v_add_u32_e32 v0, s4, v0
	v_cmp_gt_i32_e64 s[12:13], s38, v0
	s_and_b64 s[12:13], vcc, s[12:13]
	s_and_saveexec_b64 s[16:17], s[12:13]
	v_cmp_lt_i32_e64 s[12:13], -1, v36
	v_lshl_add_u32 v0, v0, 3, s97
	s_nop 0
	v_cndmask_b32_e64 v2, v123, -1, s[12:13]
	v_xor_b32_e32 v22, v2, v36
	ds_write_b64 v0, v[22:23]
	s_or_b64 exec, exec, s[16:17]
	s_bcnt1_i32_b64 s5, vcc
	v_cmp_eq_u32_e32 vcc, v35, v25
	s_add_i32 s4, s4, s5
	s_nop 0
	v_mbcnt_lo_u32_b32 v0, vcc_lo, 0
	v_mbcnt_hi_u32_b32 v0, vcc_hi, v0
	v_add_u32_e32 v0, s4, v0
	v_cmp_gt_i32_e64 s[12:13], s38, v0
	s_and_b64 s[12:13], vcc, s[12:13]
	s_and_saveexec_b64 s[16:17], s[12:13]
	v_cmp_lt_i32_e64 s[12:13], -1, v35
	v_lshl_add_u32 v0, v0, 3, s97
	s_nop 0
	v_cndmask_b32_e64 v2, v123, -1, s[12:13]
	v_xor_b32_e32 v8, v2, v35
	ds_write_b64 v0, v[8:9]
	s_or_b64 exec, exec, s[16:17]
	s_bcnt1_i32_b64 s5, vcc
	v_cmp_eq_u32_e32 vcc, v34, v25
	s_add_i32 s4, s4, s5
	s_nop 0
	v_mbcnt_lo_u32_b32 v0, vcc_lo, 0
	v_mbcnt_hi_u32_b32 v0, vcc_hi, v0
	v_add_u32_e32 v0, s4, v0
	v_cmp_gt_i32_e64 s[12:13], s38, v0
	s_and_b64 s[12:13], vcc, s[12:13]
	s_and_saveexec_b64 s[16:17], s[12:13]
	v_cmp_lt_i32_e64 s[12:13], -1, v34
	v_lshl_add_u32 v0, v0, 3, s97
	s_nop 0
	v_cndmask_b32_e64 v2, v123, -1, s[12:13]
	v_xor_b32_e32 v10, v2, v34
	ds_write_b64 v0, v[10:11]
	s_or_b64 exec, exec, s[16:17]
	s_bcnt1_i32_b64 s5, vcc
	v_cmp_eq_u32_e32 vcc, v33, v25
	s_add_i32 s4, s4, s5
	s_nop 0
	v_mbcnt_lo_u32_b32 v0, vcc_lo, 0
	v_mbcnt_hi_u32_b32 v0, vcc_hi, v0
	v_add_u32_e32 v0, s4, v0
	v_cmp_gt_i32_e64 s[12:13], s38, v0
	s_and_b64 s[12:13], vcc, s[12:13]
	s_and_saveexec_b64 s[16:17], s[12:13]
	v_cmp_lt_i32_e64 s[12:13], -1, v33
	v_lshl_add_u32 v0, v0, 3, s97
	s_nop 0
	v_cndmask_b32_e64 v2, v123, -1, s[12:13]
	v_xor_b32_e32 v16, v2, v33
	ds_write_b64 v0, v[16:17]
	s_or_b64 exec, exec, s[16:17]
	s_bcnt1_i32_b64 s5, vcc
	v_cmp_eq_u32_e32 vcc, v32, v25
	s_add_i32 s4, s4, s5
	s_nop 0
	v_mbcnt_lo_u32_b32 v0, vcc_lo, 0
	v_mbcnt_hi_u32_b32 v0, vcc_hi, v0
	v_add_u32_e32 v0, s4, v0
	v_cmp_gt_i32_e64 s[12:13], s38, v0
	s_and_b64 s[12:13], vcc, s[12:13]
	s_and_saveexec_b64 s[16:17], s[12:13]
	v_cmp_lt_i32_e64 s[12:13], -1, v32
	v_lshl_add_u32 v0, v0, 3, s97
	s_nop 0
	v_cndmask_b32_e64 v2, v123, -1, s[12:13]
	v_xor_b32_e32 v18, v2, v32
	ds_write_b64 v0, v[18:19]
	s_or_b64 exec, exec, s[16:17]
	s_bcnt1_i32_b64 s5, vcc
	v_cmp_eq_u32_e32 vcc, v31, v25
	s_add_i32 s4, s4, s5
	s_nop 0
	v_mbcnt_lo_u32_b32 v0, vcc_lo, 0
	v_mbcnt_hi_u32_b32 v0, vcc_hi, v0
	v_add_u32_e32 v0, s4, v0
	v_cmp_gt_i32_e64 s[12:13], s38, v0
	s_and_b64 s[12:13], vcc, s[12:13]
	s_and_saveexec_b64 s[16:17], s[12:13]
	v_cmp_lt_i32_e64 s[12:13], -1, v31
	v_lshl_add_u32 v0, v0, 3, s97
	s_nop 0
	v_cndmask_b32_e64 v2, v123, -1, s[12:13]
	v_xor_b32_e32 v12, v2, v31
	ds_write_b64 v0, v[12:13]
	s_or_b64 exec, exec, s[16:17]
	s_bcnt1_i32_b64 s5, vcc
	v_cmp_eq_u32_e32 vcc, v30, v25
	s_add_i32 s4, s4, s5
	s_nop 0
	v_mbcnt_lo_u32_b32 v0, vcc_lo, 0
	v_mbcnt_hi_u32_b32 v0, vcc_hi, v0
	v_add_u32_e32 v0, s4, v0
	v_cmp_gt_i32_e64 s[12:13], s38, v0
	s_and_b64 s[12:13], vcc, s[12:13]
	s_and_saveexec_b64 s[16:17], s[12:13]
	v_cmp_lt_i32_e64 s[12:13], -1, v30
	v_lshl_add_u32 v0, v0, 3, s97
	s_nop 0
	v_cndmask_b32_e64 v2, v123, -1, s[12:13]
	v_xor_b32_e32 v14, v2, v30
	ds_write_b64 v0, v[14:15]
	s_or_b64 exec, exec, s[16:17]
	s_bcnt1_i32_b64 s5, vcc
	v_cmp_eq_u32_e32 vcc, v29, v25
	s_add_i32 s4, s4, s5
	s_nop 0
	v_mbcnt_lo_u32_b32 v0, vcc_lo, 0
	v_mbcnt_hi_u32_b32 v0, vcc_hi, v0
	v_add_u32_e32 v0, s4, v0
	v_cmp_gt_i32_e64 s[12:13], s38, v0
	s_and_b64 s[12:13], vcc, s[12:13]
	s_and_saveexec_b64 s[16:17], s[12:13]
	v_cmp_lt_i32_e64 s[12:13], -1, v29
	v_lshl_add_u32 v0, v0, 3, s97
	s_nop 0
	v_cndmask_b32_e64 v2, v123, -1, s[12:13]
	v_xor_b32_e32 v4, v2, v29
	ds_write_b64 v0, v[4:5]
	s_or_b64 exec, exec, s[16:17]
	s_bcnt1_i32_b64 s5, vcc
	v_cmp_eq_u32_e32 vcc, v28, v25
	s_add_i32 s4, s4, s5
	s_nop 0
	v_mbcnt_lo_u32_b32 v0, vcc_lo, 0
	v_mbcnt_hi_u32_b32 v0, vcc_hi, v0
	v_add_u32_e32 v0, s4, v0
	v_cmp_gt_i32_e64 s[12:13], s38, v0
	s_and_b64 s[12:13], vcc, s[12:13]
	s_and_saveexec_b64 s[16:17], s[12:13]
	v_cmp_lt_i32_e64 s[12:13], -1, v28
	v_lshl_add_u32 v0, v0, 3, s97
	s_nop 0
	v_cndmask_b32_e64 v2, v123, -1, s[12:13]
	v_xor_b32_e32 v6, v2, v28
	ds_write_b64 v0, v[6:7]
	s_or_b64 exec, exec, s[16:17]
	s_bcnt1_i32_b64 s5, vcc
	v_cmp_eq_u32_e32 vcc, v27, v25
	s_add_i32 s4, s4, s5
	s_nop 0
	v_mbcnt_lo_u32_b32 v0, vcc_lo, 0
	v_mbcnt_hi_u32_b32 v0, vcc_hi, v0
	v_add_u32_e32 v0, s4, v0
	v_cmp_gt_i32_e64 s[12:13], s38, v0
	s_and_b64 s[12:13], vcc, s[12:13]
	s_and_saveexec_b64 s[16:17], s[12:13]
	v_cmp_lt_i32_e64 s[12:13], -1, v27
	v_lshl_add_u32 v2, v0, 3, s97
	s_nop 0
	v_cndmask_b32_e64 v0, v123, -1, s[12:13]
	v_xor_b32_e32 v0, v0, v27
	ds_write_b64 v2, v[0:1]
	s_or_b64 exec, exec, s[16:17]
	v_cmp_eq_u32_e64 s[12:13], v26, v25
	s_bcnt1_i32_b64 s5, vcc
	s_add_i32 s18, s4, s5
	v_mbcnt_lo_u32_b32 v0, s12, 0
	v_mbcnt_hi_u32_b32 v0, s13, v0
	v_add_u32_e32 v0, s18, v0
	v_cmp_gt_i32_e32 vcc, s38, v0
	s_and_b64 s[4:5], s[12:13], vcc
	s_and_saveexec_b64 s[16:17], s[4:5]
	v_cmp_lt_i32_e32 vcc, -1, v26
	v_lshl_add_u32 v0, v0, 3, s97
	s_nop 0
	v_cndmask_b32_e64 v2, v123, -1, vcc
	v_xor_b32_e32 v2, v2, v26
	ds_write_b64 v0, v[2:3]
	s_or_b64 exec, exec, s[16:17]
	s_branch .LBB0_484
.LBB0_456:
	s_branch .LBB0_394

; #define LDS_WAIT() asm volatile("s_waitcnt lgkmcnt(0)" ::: "memory")
; __device__ __forceinline__ unsigned ord2bits(unsigned k) { return (k & 0x80000000u) ? (k ^ 0x80000000u) : ~k; }
; __device__ __forceinline__ int topk_compact(LAS u32x2* buf, int cnt, float& tau) {
;     ...
;     tau = __uint_as_float(ord2bits(cT == 256 ? T - 1u : T));
;     LDS_WAIT();
;     return base < 256 ? base : 256;
; __device__ __forceinline__ void indexer_block16(const bf16_t* __restrict__ Z, const bf16_t* __restrict__ KI, int* __restrict__ SEL, int qb, LAS unsigned char* lds, int wave) {
;     ...
;             if (cntA > 256) { float nt; cntA = topk_compact(wbuf, cntA, nt); tau = half ? tau : nt; }
;             if (cntB > 256) { float nt; cntB = topk_compact(wbuf + 768, cntB, nt); tau = half ? nt : tau; }
.LBB0_570:
	v_cndmask_b32_e64 v0, 0, 1, s[14:15]
	v_sub_u32_e32 v0, v25, v0
	v_cmp_lt_i32_e32 vcc, -1, v0
	s_bcnt1_i32_b64 s4, s[12:13]
	s_waitcnt lgkmcnt(0)
	s_add_i32 s4, s18, s4
	v_cndmask_b32_e64 v1, v123, -1, vcc
	v_xor_b32_e32 v0, v1, v0
	s_min_u32 s75, s4, 0x100
	v_cndmask_b32_e64 v128, v0, v128, s[6:7]
	s_branch .LBB0_571

; __global__ void __launch_bounds__(512, 2) mega(Params p) {
;     ...
;             for (int base = 0; base < 512; base += nblk) {
;                 const int i = base + bid;
;                 if (i < 512) {
;     ...
;                     indexer_block16(Z, KI, SEL, i, lds, wave);
;                     indexer_block16(Z, KI, SEL, 1023 - i, lds, wave);
;     ...
;                 }
;             }
.LBB0_761:
	s_or_b64 exec, exec, s[6:7]
	s_waitcnt lgkmcnt(0)
	s_barrier
	s_cmp_lg_u32 s98, 0
	s_cbranch_scc1 .LBB0_356
	s_mov_b32 s98, 1
	s_sub_i32 s49, 0x3ff0, s49
	s_branch .Lidx_pass

; #define LAS __attribute__((address_space(3)))
; __global__ void __launch_bounds__(512, 2) mega(Params p) {
;     extern __shared__ __attribute__((aligned(16))) unsigned char smem[];
;     cg::grid_group grid = cg::this_grid();
;     LAS unsigned char* lds = (LAS unsigned char*)smem;
;     const int wave = __builtin_amdgcn_readfirstlane((int)threadIdx.x >> 6);
;     const int nblk = gridDim.x, bid = blockIdx.x, gw = bid * 8 + wave, ngw = nblk * 8;
	.amdhsa_kernel _Z4mega6Params
		.amdhsa_group_segment_fixed_size 0
		.amdhsa_private_segment_fixed_size 0
		.amdhsa_kernarg_size 376
		.amdhsa_user_sgpr_count 2
		.amdhsa_user_sgpr_dispatch_ptr 0
		.amdhsa_user_sgpr_queue_ptr 0
		.amdhsa_user_sgpr_kernarg_segment_ptr 1
		.amdhsa_user_sgpr_dispatch_id 0
		.amdhsa_user_sgpr_kernarg_preload_length 0
		.amdhsa_user_sgpr_kernarg_preload_offset 0
		.amdhsa_user_sgpr_private_segment_size 0
		.amdhsa_uses_dynamic_stack 0
		.amdhsa_enable_private_segment 0
		.amdhsa_system_sgpr_workgroup_id_x 1
		.amdhsa_system_sgpr_workgroup_id_y 0
		.amdhsa_system_sgpr_workgroup_id_z 0
		.amdhsa_system_sgpr_workgroup_info 0
		.amdhsa_system_vgpr_workitem_id 2
		.amdhsa_next_free_vgpr 249
		.amdhsa_next_free_sgpr 102
		.amdhsa_accum_offset 252
		.amdhsa_reserve_vcc 1
		.amdhsa_float_round_mode_32 0
		.amdhsa_float_round_mode_16_64 0
		.amdhsa_float_denorm_mode_32 3
		.amdhsa_float_denorm_mode_16_64 3
		.amdhsa_dx10_clamp 1
		.amdhsa_ieee_mode 1
		.amdhsa_fp16_overflow 0
		.amdhsa_tg_split 0
		.amdhsa_exception_fp_ieee_invalid_op 0
		.amdhsa_exception_fp_denorm_src 0
		.amdhsa_exception_fp_ieee_div_zero 0
		.amdhsa_exception_fp_ieee_overflow 0
		.amdhsa_exception_fp_ieee_underflow 0
		.amdhsa_exception_fp_ieee_inexact 0
		.amdhsa_exception_int_div_zero 0
	.end_amdhsa_kernel

; #define LAS __attribute__((address_space(3)))
; __global__ void __launch_bounds__(512, 2) mega(Params p) {
;     extern __shared__ __attribute__((aligned(16))) unsigned char smem[];
;     cg::grid_group grid = cg::this_grid();
;     LAS unsigned char* lds = (LAS unsigned char*)smem;
;     const int wave = __builtin_amdgcn_readfirstlane((int)threadIdx.x >> 6);
;     const int nblk = gridDim.x, bid = blockIdx.x, gw = bid * 8 + wave, ngw = nblk * 8;
amdhsa.kernels:
  - .agpr_count:     0
    .args:
      - .offset:         0
        .size:           120
        .value_kind:     by_value
      - .offset:         120
        .size:           4
        .value_kind:     hidden_block_count_x
      - .offset:         124
        .size:           4
        .value_kind:     hidden_block_count_y
      - .offset:         128
        .size:           4
        .value_kind:     hidden_block_count_z
      - .offset:         132
        .size:           2
        .value_kind:     hidden_group_size_x
      - .offset:         134
        .size:           2
        .value_kind:     hidden_group_size_y
      - .offset:         136
        .size:           2
        .value_kind:     hidden_group_size_z
      - .offset:         138
        .size:           2
        .value_kind:     hidden_remainder_x
      - .offset:         140
        .size:           2
        .value_kind:     hidden_remainder_y
      - .offset:         142
        .size:           2
        .value_kind:     hidden_remainder_z
      - .offset:         160
        .size:           8
        .value_kind:     hidden_global_offset_x
      - .offset:         168
        .size:           8
        .value_kind:     hidden_global_offset_y
      - .offset:         176
        .size:           8
        .value_kind:     hidden_global_offset_z
      - .offset:         184
        .size:           2
        .value_kind:     hidden_grid_dims
      - .offset:         208
        .size:           8
        .value_kind:     hidden_multigrid_sync_arg
      - .offset:         240
        .size:           4
        .value_kind:     hidden_dynamic_lds_size
    .group_segment_fixed_size: 0
    .kernarg_segment_align: 8
    .kernarg_segment_size: 376
    .language:       OpenCL C
    .language_version:
      - 2
      - 0
    .max_flat_workgroup_size: 512
    .name:           _Z4mega6Params
    .private_segment_fixed_size: 0
    .sgpr_count:     108
    .sgpr_spill_count: 25
    .symbol:         _Z4mega6Params.kd
    .uniform_work_group_size: 1
    .uses_dynamic_stack: false
    .vgpr_count:     249
    .vgpr_spill_count: 0
    .wavefront_size: 64
